# peel + no redundant fence + first two vmcnt waits of each tile no longer wait for the previous tile's epilogue stores (QKV, FFN-in)
# baseline (speedup 1.0000x reference)
.LBB0_490:
	s_ashr_i32 s11, s10, 31
	s_lshl_b64 s[12:13], s[10:11], 20
	v_readlane_b32 s14, v253, 25
	v_readlane_b32 s15, v253, 26
	s_add_u32 s12, s14, s12
	s_addc_u32 s13, s15, s13
	s_and_b64 s[14:15], s[34:35], exec
	s_cselect_b32 s11, s13, s17
	s_cselect_b32 s49, s12, s16
	s_ashr_i32 s9, s8, 31
	s_lshl_b64 s[14:15], s[8:9], 20
	s_add_u32 s14, s25, s14
	s_addc_u32 s15, s36, s15
	s_and_b64 s[20:21], s[34:35], exec
	s_cselect_b32 s9, s15, s19
	s_cselect_b32 s50, s14, s18
	s_add_u32 s16, s16, 0x80080
	s_addc_u32 s17, s17, 0
	s_add_u32 s51, s18, 0x100
	s_addc_u32 s52, s19, 0
	s_mov_b32 s53, -2
	s_add_u32 s18, s16, 0xfff80080
	s_addc_u32 s19, s17, -1
	s_add_i32 s54, 0, 0x10000
	s_cmp_eq_u32 s53, 28
	s_cselect_b32 s21, s11, s19
	s_cselect_b32 s20, s49, s18
	s_cselect_b32 s19, s9, s52
	s_cselect_b32 s18, s50, s51
	s_add_i32 s56, 0, 0x14000
	v_add_u32_e32 v156, s54, v141
	v_add_u32_e32 v172, s56, v141
	ds_read_b128 v[144:147], v156
	ds_read_b128 v[148:151], v156 offset:1024
	ds_read_b128 v[152:155], v156 offset:2048
	ds_read_b128 v[156:159], v156 offset:3072
	ds_read_b128 v[160:163], v172
	ds_read_b128 v[164:167], v172 offset:1024
	ds_read_b128 v[168:171], v172 offset:2048
	ds_read_b128 v[172:175], v172 offset:3072
	v_lshl_add_u64 v[208:209], s[16:17], 0, v[136:137]
	s_add_i32 m0, s39, 0xc000
	ds_read_b128 v[176:179], v143
	ds_read_b128 v[180:183], v143 offset:1024
	ds_read_b128 v[184:187], v143 offset:2048
	ds_read_b128 v[188:191], v143 offset:3072
	ds_read_b128 v[192:195], v143 offset:4096
	ds_read_b128 v[196:199], v143 offset:5120
	ds_read_b128 v[200:203], v143 offset:6144
	ds_read_b128 v[204:207], v143 offset:7168
	global_load_lds_dwordx4 v[208:209], off
	v_lshl_add_u64 v[208:209], s[16:17], 0, v[138:139]
	s_add_i32 m0, s39, 0xe000
	s_nop 0
	global_load_lds_dwordx4 v[208:209], off
	s_waitcnt vmcnt(24)
	s_waitcnt lgkmcnt(0)
	s_barrier
	s_setprio 1
	s_waitcnt lgkmcnt(0)
	v_mfma_f32_16x16x32_bf16 v[126:129], v[144:147], v[176:179], 0
	v_mfma_f32_16x16x32_bf16 v[122:125], v[152:155], v[176:179], 0
	v_mfma_f32_16x16x32_bf16 v[118:121], v[144:147], v[184:187], 0
	v_mfma_f32_16x16x32_bf16 v[114:117], v[152:155], v[184:187], 0
	v_mfma_f32_16x16x32_bf16 v[102:105], v[144:147], v[192:195], 0
	v_mfma_f32_16x16x32_bf16 v[98:101], v[152:155], v[192:195], 0
	v_mfma_f32_16x16x32_bf16 v[86:89], v[144:147], v[200:203], 0
	v_mfma_f32_16x16x32_bf16 v[82:85], v[152:155], v[200:203], 0
	v_mfma_f32_16x16x32_bf16 v[126:129], v[148:151], v[180:183], v[126:129]
	v_mfma_f32_16x16x32_bf16 v[122:125], v[156:159], v[180:183], v[122:125]
	v_mfma_f32_16x16x32_bf16 v[118:121], v[148:151], v[188:191], v[118:121]
	v_mfma_f32_16x16x32_bf16 v[114:117], v[156:159], v[188:191], v[114:117]
	v_mfma_f32_16x16x32_bf16 v[102:105], v[148:151], v[196:199], v[102:105]
	v_mfma_f32_16x16x32_bf16 v[98:101], v[156:159], v[196:199], v[98:101]
	v_mfma_f32_16x16x32_bf16 v[86:89], v[148:151], v[204:207], v[86:89]
	v_mfma_f32_16x16x32_bf16 v[82:85], v[156:159], v[204:207], v[82:85]
	s_setprio 0
	s_setprio 1
	v_mfma_f32_16x16x32_bf16 v[110:113], v[160:163], v[176:179], 0
	v_mfma_f32_16x16x32_bf16 v[106:109], v[168:171], v[176:179], 0
	v_mfma_f32_16x16x32_bf16 v[94:97], v[160:163], v[184:187], 0
	v_mfma_f32_16x16x32_bf16 v[90:93], v[168:171], v[184:187], 0
	v_mfma_f32_16x16x32_bf16 v[78:81], v[160:163], v[192:195], 0
	v_mfma_f32_16x16x32_bf16 v[74:77], v[168:171], v[192:195], 0
	v_mfma_f32_16x16x32_bf16 v[70:73], v[160:163], v[200:203], 0
	v_mfma_f32_16x16x32_bf16 v[66:69], v[168:171], v[200:203], 0
	v_mfma_f32_16x16x32_bf16 v[110:113], v[164:167], v[180:183], v[110:113]
	v_mfma_f32_16x16x32_bf16 v[106:109], v[172:175], v[180:183], v[106:109]
	v_mfma_f32_16x16x32_bf16 v[94:97], v[164:167], v[188:191], v[94:97]
	v_mfma_f32_16x16x32_bf16 v[90:93], v[172:175], v[188:191], v[90:93]
	v_mfma_f32_16x16x32_bf16 v[78:81], v[164:167], v[196:199], v[78:81]
	v_mfma_f32_16x16x32_bf16 v[74:77], v[172:175], v[196:199], v[74:77]
	v_mfma_f32_16x16x32_bf16 v[70:73], v[164:167], v[204:207], v[70:73]
	v_mfma_f32_16x16x32_bf16 v[66:69], v[172:175], v[204:207], v[66:69]
	s_setprio 0
	s_barrier
	s_add_i32 s54, s54, s37
	v_lshl_add_u64 v[208:209], s[18:19], 0, v[0:1]
	s_mov_b32 m0, s54
	ds_read_b128 v[176:179], v143 offset:16384
	ds_read_b128 v[180:183], v143 offset:17408
	ds_read_b128 v[184:187], v143 offset:18432
	ds_read_b128 v[188:191], v143 offset:19456
	ds_read_b128 v[192:195], v143 offset:20480
	ds_read_b128 v[196:199], v143 offset:21504
	ds_read_b128 v[200:203], v143 offset:22528
	ds_read_b128 v[204:207], v143 offset:23552
	global_load_lds_dwordx4 v[208:209], off
	s_add_i32 m0, s54, 0x2000
	s_add_u32 s54, s18, 0x80000
	v_lshl_add_u64 v[220:221], s[18:19], 0, v[130:131]
	s_addc_u32 s55, s19, 0
	s_add_i32 s56, s56, s37
	global_load_lds_dwordx4 v[220:221], off
	v_lshl_add_u64 v[222:223], s[54:55], 0, v[0:1]
	s_mov_b32 m0, s56
	v_lshl_add_u64 v[224:225], s[20:21], 0, v[132:133]
	global_load_lds_dwordx4 v[222:223], off
	v_lshl_add_u64 v[222:223], s[54:55], 0, v[130:131]
	s_add_i32 m0, s56, 0x2000
	s_nop 0
	global_load_lds_dwordx4 v[222:223], off
	v_lshl_add_u64 v[222:223], s[20:21], 0, v[134:135]
	s_mov_b32 m0, s39
	s_nop 0
	global_load_lds_dwordx4 v[222:223], off
	s_mov_b32 m0, s40
	s_nop 0
	global_load_lds_dwordx4 v[224:225], off
	s_waitcnt vmcnt(24)
	s_waitcnt lgkmcnt(0)
	s_barrier
	s_setprio 1
	s_waitcnt lgkmcnt(0)
	v_mfma_f32_16x16x32_bf16 v[62:65], v[144:147], v[176:179], 0
	v_mfma_f32_16x16x32_bf16 v[58:61], v[152:155], v[176:179], 0
	v_mfma_f32_16x16x32_bf16 v[54:57], v[144:147], v[184:187], 0
	v_mfma_f32_16x16x32_bf16 v[50:53], v[152:155], v[184:187], 0
	v_mfma_f32_16x16x32_bf16 v[38:41], v[144:147], v[192:195], 0
	v_mfma_f32_16x16x32_bf16 v[34:37], v[152:155], v[192:195], 0
	v_mfma_f32_16x16x32_bf16 v[22:25], v[144:147], v[200:203], 0
	v_mfma_f32_16x16x32_bf16 v[18:21], v[152:155], v[200:203], 0
	v_mfma_f32_16x16x32_bf16 v[62:65], v[148:151], v[180:183], v[62:65]
	v_mfma_f32_16x16x32_bf16 v[58:61], v[156:159], v[180:183], v[58:61]
	v_mfma_f32_16x16x32_bf16 v[54:57], v[148:151], v[188:191], v[54:57]
	v_mfma_f32_16x16x32_bf16 v[50:53], v[156:159], v[188:191], v[50:53]
	v_mfma_f32_16x16x32_bf16 v[38:41], v[148:151], v[196:199], v[38:41]
	v_mfma_f32_16x16x32_bf16 v[34:37], v[156:159], v[196:199], v[34:37]
	v_mfma_f32_16x16x32_bf16 v[22:25], v[148:151], v[204:207], v[22:25]
	v_mfma_f32_16x16x32_bf16 v[18:21], v[156:159], v[204:207], v[18:21]
	s_setprio 0
	s_setprio 1
	v_mfma_f32_16x16x32_bf16 v[46:49], v[160:163], v[176:179], 0
	v_mfma_f32_16x16x32_bf16 v[42:45], v[168:171], v[176:179], 0
	v_mfma_f32_16x16x32_bf16 v[30:33], v[160:163], v[184:187], 0
	v_mfma_f32_16x16x32_bf16 v[26:29], v[168:171], v[184:187], 0
	v_mfma_f32_16x16x32_bf16 v[14:17], v[160:163], v[192:195], 0
	v_mfma_f32_16x16x32_bf16 v[10:13], v[168:171], v[192:195], 0
	v_mfma_f32_16x16x32_bf16 v[6:9], v[160:163], v[200:203], 0
	v_mfma_f32_16x16x32_bf16 v[2:5], v[168:171], v[200:203], 0
	v_mfma_f32_16x16x32_bf16 v[46:49], v[164:167], v[180:183], v[46:49]
	v_mfma_f32_16x16x32_bf16 v[42:45], v[172:175], v[180:183], v[42:45]
	v_mfma_f32_16x16x32_bf16 v[30:33], v[164:167], v[188:191], v[30:33]
	v_mfma_f32_16x16x32_bf16 v[26:29], v[172:175], v[188:191], v[26:29]
	v_mfma_f32_16x16x32_bf16 v[14:17], v[164:167], v[196:199], v[14:17]
	v_mfma_f32_16x16x32_bf16 v[10:13], v[172:175], v[196:199], v[10:13]
	v_mfma_f32_16x16x32_bf16 v[6:9], v[164:167], v[204:207], v[6:9]
	v_mfma_f32_16x16x32_bf16 v[2:5], v[172:175], v[204:207], v[2:5]
	s_setprio 0
	s_barrier
	s_add_i32 s54, 0, 0x18000
	s_add_i32 s55, 0, 0x1c000
	v_add_u32_e32 v156, s54, v141
	v_add_u32_e32 v172, s55, v141
	ds_read_b128 v[144:147], v156
	ds_read_b128 v[148:151], v156 offset:1024
	ds_read_b128 v[152:155], v156 offset:2048
	ds_read_b128 v[156:159], v156 offset:3072
	ds_read_b128 v[160:163], v172
	ds_read_b128 v[164:167], v172 offset:1024
	ds_read_b128 v[168:171], v172 offset:2048
	ds_read_b128 v[172:175], v172 offset:3072
	s_add_u32 s20, s20, 0x80000
	s_addc_u32 s21, s21, 0
	s_mov_b32 m0, s41
	v_lshl_add_u64 v[226:227], s[20:21], 0, v[134:135]
	ds_read_b128 v[176:179], v143 offset:32768
	ds_read_b128 v[180:183], v143 offset:33792
	ds_read_b128 v[184:187], v143 offset:34816
	ds_read_b128 v[188:191], v143 offset:35840
	ds_read_b128 v[192:195], v143 offset:36864
	ds_read_b128 v[196:199], v143 offset:37888
	ds_read_b128 v[200:203], v143 offset:38912
	ds_read_b128 v[204:207], v143 offset:39936
	global_load_lds_dwordx4 v[226:227], off
	v_lshl_add_u64 v[226:227], s[20:21], 0, v[132:133]
	s_mov_b32 m0, s44
	s_nop 0
	global_load_lds_dwordx4 v[226:227], off
	s_waitcnt vmcnt(8)
	s_waitcnt lgkmcnt(0)
	s_barrier
	s_setprio 1
	s_waitcnt lgkmcnt(0)
	v_mfma_f32_16x16x32_bf16 v[126:129], v[144:147], v[176:179], v[126:129]
	v_mfma_f32_16x16x32_bf16 v[122:125], v[152:155], v[176:179], v[122:125]
	v_mfma_f32_16x16x32_bf16 v[118:121], v[144:147], v[184:187], v[118:121]
	v_mfma_f32_16x16x32_bf16 v[114:117], v[152:155], v[184:187], v[114:117]
	v_mfma_f32_16x16x32_bf16 v[102:105], v[144:147], v[192:195], v[102:105]
	v_mfma_f32_16x16x32_bf16 v[98:101], v[152:155], v[192:195], v[98:101]
	v_mfma_f32_16x16x32_bf16 v[86:89], v[144:147], v[200:203], v[86:89]
	v_mfma_f32_16x16x32_bf16 v[82:85], v[152:155], v[200:203], v[82:85]
	v_mfma_f32_16x16x32_bf16 v[126:129], v[148:151], v[180:183], v[126:129]
	v_mfma_f32_16x16x32_bf16 v[122:125], v[156:159], v[180:183], v[122:125]
	v_mfma_f32_16x16x32_bf16 v[118:121], v[148:151], v[188:191], v[118:121]
	v_mfma_f32_16x16x32_bf16 v[114:117], v[156:159], v[188:191], v[114:117]
	v_mfma_f32_16x16x32_bf16 v[102:105], v[148:151], v[196:199], v[102:105]
	v_mfma_f32_16x16x32_bf16 v[98:101], v[156:159], v[196:199], v[98:101]
	v_mfma_f32_16x16x32_bf16 v[86:89], v[148:151], v[204:207], v[86:89]
	v_mfma_f32_16x16x32_bf16 v[82:85], v[156:159], v[204:207], v[82:85]
	s_setprio 0
	s_setprio 1
	v_mfma_f32_16x16x32_bf16 v[110:113], v[160:163], v[176:179], v[110:113]
	v_mfma_f32_16x16x32_bf16 v[106:109], v[168:171], v[176:179], v[106:109]
	v_mfma_f32_16x16x32_bf16 v[94:97], v[160:163], v[184:187], v[94:97]
	v_mfma_f32_16x16x32_bf16 v[90:93], v[168:171], v[184:187], v[90:93]
	v_mfma_f32_16x16x32_bf16 v[78:81], v[160:163], v[192:195], v[78:81]
	v_mfma_f32_16x16x32_bf16 v[74:77], v[168:171], v[192:195], v[74:77]
	v_mfma_f32_16x16x32_bf16 v[70:73], v[160:163], v[200:203], v[70:73]
	v_mfma_f32_16x16x32_bf16 v[66:69], v[168:171], v[200:203], v[66:69]
	v_mfma_f32_16x16x32_bf16 v[110:113], v[164:167], v[180:183], v[110:113]
	v_mfma_f32_16x16x32_bf16 v[106:109], v[172:175], v[180:183], v[106:109]
	v_mfma_f32_16x16x32_bf16 v[94:97], v[164:167], v[188:191], v[94:97]
	v_mfma_f32_16x16x32_bf16 v[90:93], v[172:175], v[188:191], v[90:93]
	v_mfma_f32_16x16x32_bf16 v[78:81], v[164:167], v[196:199], v[78:81]
	v_mfma_f32_16x16x32_bf16 v[74:77], v[172:175], v[196:199], v[74:77]
	v_mfma_f32_16x16x32_bf16 v[70:73], v[164:167], v[204:207], v[70:73]
	v_mfma_f32_16x16x32_bf16 v[66:69], v[172:175], v[204:207], v[66:69]
	s_setprio 0
	s_barrier
	s_add_i32 s20, s54, s37
	v_lshl_add_u64 v[208:209], v[208:209], 0, s[2:3]
	s_mov_b32 m0, s20
	ds_read_b128 v[176:179], v143 offset:49152
	ds_read_b128 v[180:183], v143 offset:50176
	ds_read_b128 v[184:187], v143 offset:51200
	ds_read_b128 v[188:191], v143 offset:52224
	ds_read_b128 v[192:195], v143 offset:53248
	ds_read_b128 v[196:199], v143 offset:54272
	ds_read_b128 v[200:203], v143 offset:55296
	ds_read_b128 v[204:207], v143 offset:56320
	global_load_lds_dwordx4 v[208:209], off
	s_add_i32 m0, s20, 0x2000
	s_add_u32 s18, s18, 0x80080
	v_lshl_add_u64 v[208:209], v[220:221], 0, s[2:3]
	s_addc_u32 s19, s19, 0
	s_add_i32 s20, s55, s37
	global_load_lds_dwordx4 v[208:209], off
	v_lshl_add_u64 v[208:209], s[18:19], 0, v[0:1]
	s_mov_b32 m0, s20
	s_nop 0
	global_load_lds_dwordx4 v[208:209], off
	v_lshl_add_u64 v[208:209], s[18:19], 0, v[130:131]
	s_add_i32 m0, s20, 0x2000
	s_nop 0
	global_load_lds_dwordx4 v[208:209], off
	v_lshl_add_u64 v[208:209], v[222:223], 0, s[2:3]
	s_mov_b32 m0, s45
	s_nop 0
	global_load_lds_dwordx4 v[208:209], off
	v_lshl_add_u64 v[208:209], v[224:225], 0, s[2:3]
	s_mov_b32 m0, s46
	s_nop 0
	global_load_lds_dwordx4 v[208:209], off
	s_waitcnt vmcnt(8)
	s_waitcnt lgkmcnt(0)
	s_barrier
	s_setprio 1
	s_waitcnt lgkmcnt(0)
	v_mfma_f32_16x16x32_bf16 v[62:65], v[144:147], v[176:179], v[62:65]
	v_mfma_f32_16x16x32_bf16 v[58:61], v[152:155], v[176:179], v[58:61]
	v_mfma_f32_16x16x32_bf16 v[54:57], v[144:147], v[184:187], v[54:57]
	v_mfma_f32_16x16x32_bf16 v[50:53], v[152:155], v[184:187], v[50:53]
	v_mfma_f32_16x16x32_bf16 v[38:41], v[144:147], v[192:195], v[38:41]
	v_mfma_f32_16x16x32_bf16 v[34:37], v[152:155], v[192:195], v[34:37]
	v_mfma_f32_16x16x32_bf16 v[22:25], v[144:147], v[200:203], v[22:25]
	v_mfma_f32_16x16x32_bf16 v[18:21], v[152:155], v[200:203], v[18:21]
	v_mfma_f32_16x16x32_bf16 v[62:65], v[148:151], v[180:183], v[62:65]
	v_mfma_f32_16x16x32_bf16 v[58:61], v[156:159], v[180:183], v[58:61]
	v_mfma_f32_16x16x32_bf16 v[54:57], v[148:151], v[188:191], v[54:57]
	v_mfma_f32_16x16x32_bf16 v[50:53], v[156:159], v[188:191], v[50:53]
	v_mfma_f32_16x16x32_bf16 v[38:41], v[148:151], v[196:199], v[38:41]
	v_mfma_f32_16x16x32_bf16 v[34:37], v[156:159], v[196:199], v[34:37]
	v_mfma_f32_16x16x32_bf16 v[22:25], v[148:151], v[204:207], v[22:25]
	v_mfma_f32_16x16x32_bf16 v[18:21], v[156:159], v[204:207], v[18:21]
	s_setprio 0
	s_setprio 1
	v_mfma_f32_16x16x32_bf16 v[46:49], v[160:163], v[176:179], v[46:49]
	v_mfma_f32_16x16x32_bf16 v[42:45], v[168:171], v[176:179], v[42:45]
	v_mfma_f32_16x16x32_bf16 v[30:33], v[160:163], v[184:187], v[30:33]
	v_mfma_f32_16x16x32_bf16 v[26:29], v[168:171], v[184:187], v[26:29]
	v_mfma_f32_16x16x32_bf16 v[14:17], v[160:163], v[192:195], v[14:17]
	v_mfma_f32_16x16x32_bf16 v[10:13], v[168:171], v[192:195], v[10:13]
	v_mfma_f32_16x16x32_bf16 v[6:9], v[160:163], v[200:203], v[6:9]
	v_mfma_f32_16x16x32_bf16 v[2:5], v[168:171], v[200:203], v[2:5]
	v_mfma_f32_16x16x32_bf16 v[46:49], v[164:167], v[180:183], v[46:49]
	v_mfma_f32_16x16x32_bf16 v[42:45], v[172:175], v[180:183], v[42:45]
	v_mfma_f32_16x16x32_bf16 v[30:33], v[164:167], v[188:191], v[30:33]
	v_mfma_f32_16x16x32_bf16 v[26:29], v[172:175], v[188:191], v[26:29]
	v_mfma_f32_16x16x32_bf16 v[14:17], v[164:167], v[196:199], v[14:17]
	v_mfma_f32_16x16x32_bf16 v[10:13], v[172:175], v[196:199], v[10:13]
	v_mfma_f32_16x16x32_bf16 v[6:9], v[164:167], v[204:207], v[6:9]
	v_mfma_f32_16x16x32_bf16 v[2:5], v[172:175], v[204:207], v[2:5]
	s_setprio 0
	s_barrier
	s_add_i32 s53, s53, 2
	s_add_u32 s16, s16, 0x100
	s_addc_u32 s17, s17, 0
	s_add_u32 s51, s51, 0x100
	s_addc_u32 s52, s52, 0
	s_cmp_gt_u32 s53, 29
	s_cbranch_scc1 .Lpeel_done_0

.LBB0_1559:
	v_and_b32_e32 v17, 15, v16
	v_lshl_or_b32 v18, s5, 6, v17
	v_ashrrev_i32_e32 v20, 6, v16
	s_lshl_b32 s5, s5, 13
	v_lshl_add_u32 v22, v20, 10, s5
	s_lshl_b32 s5, s4, 5
	s_and_b32 s8, s5, 0x60
	s_add_i32 m0, s17, 0x18000
	v_lshl_add_u64 v[8:9], v[8:9], 0, s[2:3]
	s_lshr_b32 s5, s8, 3
	s_waitcnt vmcnt(2)
	s_barrier
	global_load_lds_dwordx4 v[8:9], off
	v_lshl_add_u64 v[6:7], v[6:7], 0, s[2:3]
	s_add_i32 m0, s17, 0x1a000
	s_add_i32 s46, s17, 0x8000
	s_add_i32 s47, s17, 0xa000
	global_load_lds_dwordx4 v[6:7], off
	v_lshl_add_u64 v[2:3], v[2:3], 0, s[2:3]
	s_mov_b32 m0, s46
	s_add_u32 s6, s20, 0x80080
	global_load_lds_dwordx4 v[2:3], off
	v_lshl_add_u64 v[2:3], v[4:5], 0, s[2:3]
	s_mov_b32 m0, s47
	s_addc_u32 s7, s21, 0
	global_load_lds_dwordx4 v[2:3], off
	s_add_i32 m0, s17, 0x1c000
	v_lshl_add_u64 v[2:3], s[6:7], 0, v[0:1]
	global_load_lds_dwordx4 v[2:3], off
	v_lshl_add_u64 v[2:3], s[6:7], 0, v[130:131]
	s_add_i32 m0, s17, 0x1e000
	v_ashrrev_i32_e32 v19, 1, v16
	global_load_lds_dwordx4 v[2:3], off
	v_and_b32_e32 v19, -8, v19
	v_or_b32_e32 v2, 16, v18
	v_add_u32_e32 v161, s8, v19
	v_ashrrev_i32_e32 v19, 31, v18
	v_ashrrev_i32_e32 v3, 31, v2
	v_lshlrev_b64 v[136:137], 7, v[18:19]
	v_lshlrev_b64 v[138:139], 7, v[2:3]
	v_or_b32_e32 v2, 32, v18
	s_mov_b64 s[6:7], 0x4000
	v_ashrrev_i32_e32 v3, 31, v2
	v_lshl_add_u64 v[144:145], v[136:137], 0, s[6:7]
	s_mov_b64 s[6:7], 0x4800
	v_lshlrev_b64 v[140:141], 7, v[2:3]
	v_or_b32_e32 v2, 48, v18
	v_lshl_add_u64 v[146:147], v[136:137], 0, s[6:7]
	s_mov_b64 s[6:7], 0x5000
	v_ashrrev_i32_e32 v3, 31, v2
	v_lshl_add_u64 v[148:149], v[136:137], 0, s[6:7]
	s_mov_b64 s[6:7], 0x5800
	v_lshlrev_b64 v[142:143], 7, v[2:3]
	v_lshl_add_u64 v[150:151], v[136:137], 0, s[6:7]
	v_and_b32_e32 v2, 56, v161
	v_readlane_b32 s6, v254, 48
	v_lshlrev_b32_e32 v2, 1, v2
	v_mov_b32_e32 v3, v1
	v_readlane_b32 s7, v254, 49
	v_and_b32_e32 v21, 48, v16
	v_lshlrev_b32_e32 v16, 2, v16
	v_lshl_add_u64 v[152:153], s[6:7], 0, v[2:3]
	v_lshlrev_b32_e32 v2, 15, v13
	v_and_b32_e32 v2, 0xffff0000, v2
	v_lshl_add_u32 v2, v14, 12, v2
	v_and_b32_e32 v3, 1, v13
	v_lshl_or_b32 v2, v3, 6, v2
	v_lshl_add_u32 v154, v15, 1, v2
	v_lshlrev_b32_e32 v2, 15, v10
	v_and_b32_e32 v2, 0xffff0000, v2
	v_lshl_or_b32 v17, v17, 6, v21
	v_and_b32_e32 v16, 32, v16
	s_waitcnt vmcnt(6)
	v_lshl_add_u32 v2, v11, 12, v2
	v_and_b32_e32 v3, 1, v10
	v_bitop3_b32 v21, v17, v22, v16 bitop3:0xde
	v_add_lshl_u32 v20, s5, v20, 10
	s_cmp_lt_u32 s4, 4
	v_lshl_or_b32 v2, v3, 6, v2
	v_bitop3_b32 v160, v17, v20, v16 bitop3:0xde
	s_cselect_b64 s[4:5], -1, 0
	s_ashr_i32 s48, s25, 31
	v_mov_b32_e32 v155, v1
	v_lshl_add_u32 v156, v12, 1, v2
	v_mov_b32_e32 v157, v1
	s_mov_b32 s49, 0
	v_add_u32_e32 v162, 0, v21
	s_barrier
	s_waitcnt vmcnt(0)
	s_branch .LBB0_1562

.LBB0_1564:
	s_ashr_i32 s9, s8, 31
	s_lshl_b64 s[10:11], s[8:9], 20
	v_readlane_b32 s12, v253, 25
	v_readlane_b32 s13, v253, 26
	s_add_u32 s10, s12, s10
	s_addc_u32 s11, s13, s11
	s_and_b64 s[12:13], s[34:35], exec
	s_cselect_b32 s9, s11, s19
	s_cselect_b32 s15, s10, s18
	s_ashr_i32 s7, s6, 31
	s_lshl_b64 s[12:13], s[6:7], 20
	s_add_u32 s12, s37, s12
	s_addc_u32 s13, s38, s13
	s_and_b64 s[22:23], s[34:35], exec
	s_cselect_b32 s7, s13, s21
	s_cselect_b32 s50, s12, s20
	s_add_u32 s18, s18, 0x80080
	s_addc_u32 s19, s19, 0
	s_add_u32 s51, s20, 0x100
	s_addc_u32 s52, s21, 0
	s_mov_b32 s53, -2
	s_add_u32 s20, s18, 0xfff80080
	s_addc_u32 s21, s19, -1
	s_add_i32 s54, 0, 0x10000
	s_cmp_eq_u32 s53, 28
	s_cselect_b32 s23, s9, s21
	s_cselect_b32 s22, s15, s20
	v_add_u32_e32 v158, s54, v160
	s_cselect_b32 s21, s7, s52
	s_cselect_b32 s20, s50, s51
	s_add_i32 s56, 0, 0x14000
	ds_read_b128 v[164:167], v158
	ds_read_b128 v[168:171], v158 offset:1024
	ds_read_b128 v[172:175], v158 offset:2048
	ds_read_b128 v[176:179], v158 offset:3072
	v_add_u32_e32 v158, s56, v160
	ds_read_b128 v[180:183], v158
	ds_read_b128 v[184:187], v158 offset:1024
	ds_read_b128 v[188:191], v158 offset:2048
	ds_read_b128 v[192:195], v158 offset:3072
	v_lshl_add_u64 v[158:159], s[18:19], 0, v[154:155]
	s_add_i32 m0, s17, 0xc000
	ds_read_b128 v[196:199], v162
	ds_read_b128 v[200:203], v162 offset:1024
	ds_read_b128 v[204:207], v162 offset:2048
	ds_read_b128 v[220:223], v162 offset:3072
	ds_read_b128 v[224:227], v162 offset:4096
	ds_read_b128 v[228:231], v162 offset:5120
	ds_read_b128 v[232:235], v162 offset:6144
	ds_read_b128 v[236:239], v162 offset:7168
	global_load_lds_dwordx4 v[158:159], off
	v_lshl_add_u64 v[158:159], s[18:19], 0, v[156:157]
	s_add_i32 m0, s17, 0xe000
	s_nop 0
	global_load_lds_dwordx4 v[158:159], off
	s_waitcnt vmcnt(16)
	s_waitcnt lgkmcnt(0)
	s_barrier
	s_setprio 1
	s_waitcnt lgkmcnt(0)
	v_mfma_f32_16x16x32_bf16 v[122:125], v[164:167], v[196:199], 0
	v_mfma_f32_16x16x32_bf16 v[114:117], v[172:175], v[196:199], 0
	v_mfma_f32_16x16x32_bf16 v[106:109], v[164:167], v[204:207], 0
	v_mfma_f32_16x16x32_bf16 v[98:101], v[172:175], v[204:207], 0
	v_mfma_f32_16x16x32_bf16 v[90:93], v[164:167], v[224:227], 0
	v_mfma_f32_16x16x32_bf16 v[82:85], v[172:175], v[224:227], 0
	v_mfma_f32_16x16x32_bf16 v[74:77], v[164:167], v[232:235], 0
	v_mfma_f32_16x16x32_bf16 v[66:69], v[172:175], v[232:235], 0
	v_mfma_f32_16x16x32_bf16 v[122:125], v[168:171], v[200:203], v[122:125]
	v_mfma_f32_16x16x32_bf16 v[114:117], v[176:179], v[200:203], v[114:117]
	v_mfma_f32_16x16x32_bf16 v[106:109], v[168:171], v[220:223], v[106:109]
	v_mfma_f32_16x16x32_bf16 v[98:101], v[176:179], v[220:223], v[98:101]
	v_mfma_f32_16x16x32_bf16 v[90:93], v[168:171], v[228:231], v[90:93]
	v_mfma_f32_16x16x32_bf16 v[82:85], v[176:179], v[228:231], v[82:85]
	v_mfma_f32_16x16x32_bf16 v[74:77], v[168:171], v[236:239], v[74:77]
	v_mfma_f32_16x16x32_bf16 v[66:69], v[176:179], v[236:239], v[66:69]
	s_setprio 0
	s_setprio 1
	v_mfma_f32_16x16x32_bf16 v[126:129], v[180:183], v[196:199], 0
	v_mfma_f32_16x16x32_bf16 v[118:121], v[188:191], v[196:199], 0
	v_mfma_f32_16x16x32_bf16 v[110:113], v[180:183], v[204:207], 0
	v_mfma_f32_16x16x32_bf16 v[102:105], v[188:191], v[204:207], 0
	v_mfma_f32_16x16x32_bf16 v[94:97], v[180:183], v[224:227], 0
	v_mfma_f32_16x16x32_bf16 v[86:89], v[188:191], v[224:227], 0
	v_mfma_f32_16x16x32_bf16 v[78:81], v[180:183], v[232:235], 0
	v_mfma_f32_16x16x32_bf16 v[70:73], v[188:191], v[232:235], 0
	v_mfma_f32_16x16x32_bf16 v[126:129], v[184:187], v[200:203], v[126:129]
	v_mfma_f32_16x16x32_bf16 v[118:121], v[192:195], v[200:203], v[118:121]
	v_mfma_f32_16x16x32_bf16 v[110:113], v[184:187], v[220:223], v[110:113]
	v_mfma_f32_16x16x32_bf16 v[102:105], v[192:195], v[220:223], v[102:105]
	v_mfma_f32_16x16x32_bf16 v[94:97], v[184:187], v[228:231], v[94:97]
	v_mfma_f32_16x16x32_bf16 v[86:89], v[192:195], v[228:231], v[86:89]
	v_mfma_f32_16x16x32_bf16 v[78:81], v[184:187], v[236:239], v[78:81]
	v_mfma_f32_16x16x32_bf16 v[70:73], v[192:195], v[236:239], v[70:73]
	s_setprio 0
	s_barrier
	s_add_i32 s54, s54, s41
	v_lshl_add_u64 v[158:159], s[20:21], 0, v[0:1]
	s_mov_b32 m0, s54
	ds_read_b128 v[196:199], v162 offset:16384
	ds_read_b128 v[200:203], v162 offset:17408
	ds_read_b128 v[204:207], v162 offset:18432
	ds_read_b128 v[220:223], v162 offset:19456
	ds_read_b128 v[224:227], v162 offset:20480
	ds_read_b128 v[228:231], v162 offset:21504
	ds_read_b128 v[232:235], v162 offset:22528
	ds_read_b128 v[236:239], v162 offset:23552
	global_load_lds_dwordx4 v[158:159], off
	s_add_i32 m0, s54, 0x2000
	s_add_u32 s54, s20, 0x80000
	v_lshl_add_u64 v[208:209], s[20:21], 0, v[130:131]
	s_addc_u32 s55, s21, 0
	s_add_i32 s56, s56, s41
	global_load_lds_dwordx4 v[208:209], off
	v_lshl_add_u64 v[216:217], s[54:55], 0, v[0:1]
	s_mov_b32 m0, s56
	v_lshl_add_u64 v[244:245], s[22:23], 0, v[132:133]
	global_load_lds_dwordx4 v[216:217], off
	v_lshl_add_u64 v[216:217], s[54:55], 0, v[130:131]
	s_add_i32 m0, s56, 0x2000
	s_nop 0
	global_load_lds_dwordx4 v[216:217], off
	v_lshl_add_u64 v[216:217], s[22:23], 0, v[134:135]
	s_mov_b32 m0, s17
	s_nop 0
	global_load_lds_dwordx4 v[216:217], off
	s_mov_b32 m0, s43
	s_nop 0
	global_load_lds_dwordx4 v[244:245], off
	s_waitcnt vmcnt(16)
	s_waitcnt lgkmcnt(0)
	s_barrier
	s_setprio 1
	s_waitcnt lgkmcnt(0)
	v_mfma_f32_16x16x32_bf16 v[58:61], v[164:167], v[196:199], 0
	v_mfma_f32_16x16x32_bf16 v[50:53], v[172:175], v[196:199], 0
	v_mfma_f32_16x16x32_bf16 v[42:45], v[164:167], v[204:207], 0
	v_mfma_f32_16x16x32_bf16 v[34:37], v[172:175], v[204:207], 0
	v_mfma_f32_16x16x32_bf16 v[26:29], v[164:167], v[224:227], 0
	v_mfma_f32_16x16x32_bf16 v[18:21], v[172:175], v[224:227], 0
	v_mfma_f32_16x16x32_bf16 v[10:13], v[164:167], v[232:235], 0
	v_mfma_f32_16x16x32_bf16 v[2:5], v[172:175], v[232:235], 0
	v_mfma_f32_16x16x32_bf16 v[58:61], v[168:171], v[200:203], v[58:61]
	v_mfma_f32_16x16x32_bf16 v[50:53], v[176:179], v[200:203], v[50:53]
	v_mfma_f32_16x16x32_bf16 v[42:45], v[168:171], v[220:223], v[42:45]
	v_mfma_f32_16x16x32_bf16 v[34:37], v[176:179], v[220:223], v[34:37]
	v_mfma_f32_16x16x32_bf16 v[26:29], v[168:171], v[228:231], v[26:29]
	v_mfma_f32_16x16x32_bf16 v[18:21], v[176:179], v[228:231], v[18:21]
	v_mfma_f32_16x16x32_bf16 v[10:13], v[168:171], v[236:239], v[10:13]
	v_mfma_f32_16x16x32_bf16 v[2:5], v[176:179], v[236:239], v[2:5]
	s_setprio 0
	s_setprio 1
	v_mfma_f32_16x16x32_bf16 v[62:65], v[180:183], v[196:199], 0
	v_mfma_f32_16x16x32_bf16 v[54:57], v[188:191], v[196:199], 0
	v_mfma_f32_16x16x32_bf16 v[46:49], v[180:183], v[204:207], 0
	v_mfma_f32_16x16x32_bf16 v[38:41], v[188:191], v[204:207], 0
	v_mfma_f32_16x16x32_bf16 v[30:33], v[180:183], v[224:227], 0
	v_mfma_f32_16x16x32_bf16 v[22:25], v[188:191], v[224:227], 0
	v_mfma_f32_16x16x32_bf16 v[14:17], v[180:183], v[232:235], 0
	v_mfma_f32_16x16x32_bf16 v[6:9], v[188:191], v[232:235], 0
	v_mfma_f32_16x16x32_bf16 v[62:65], v[184:187], v[200:203], v[62:65]
	v_mfma_f32_16x16x32_bf16 v[54:57], v[192:195], v[200:203], v[54:57]
	v_mfma_f32_16x16x32_bf16 v[46:49], v[184:187], v[220:223], v[46:49]
	v_mfma_f32_16x16x32_bf16 v[38:41], v[192:195], v[220:223], v[38:41]
	v_mfma_f32_16x16x32_bf16 v[30:33], v[184:187], v[228:231], v[30:33]
	v_mfma_f32_16x16x32_bf16 v[22:25], v[192:195], v[228:231], v[22:25]
	v_mfma_f32_16x16x32_bf16 v[14:17], v[184:187], v[236:239], v[14:17]
	v_mfma_f32_16x16x32_bf16 v[6:9], v[192:195], v[236:239], v[6:9]
	s_setprio 0
	s_barrier
	s_add_i32 s54, 0, 0x18000
	v_add_u32_e32 v163, s54, v160
	s_add_i32 s55, 0, 0x1c000
	ds_read_b128 v[164:167], v163
	ds_read_b128 v[168:171], v163 offset:1024
	ds_read_b128 v[172:175], v163 offset:2048
	ds_read_b128 v[176:179], v163 offset:3072
	v_add_u32_e32 v163, s55, v160
	ds_read_b128 v[180:183], v163
	ds_read_b128 v[184:187], v163 offset:1024
	ds_read_b128 v[188:191], v163 offset:2048
	ds_read_b128 v[192:195], v163 offset:3072
	s_add_u32 s22, s22, 0x80000
	s_addc_u32 s23, s23, 0
	s_mov_b32 m0, s44
	v_lshl_add_u64 v[246:247], s[22:23], 0, v[134:135]
	ds_read_b128 v[196:199], v162 offset:32768
	ds_read_b128 v[200:203], v162 offset:33792
	ds_read_b128 v[204:207], v162 offset:34816
	ds_read_b128 v[220:223], v162 offset:35840
	ds_read_b128 v[224:227], v162 offset:36864
	ds_read_b128 v[228:231], v162 offset:37888
	ds_read_b128 v[232:235], v162 offset:38912
	ds_read_b128 v[236:239], v162 offset:39936
	global_load_lds_dwordx4 v[246:247], off
	v_lshl_add_u64 v[246:247], s[22:23], 0, v[132:133]
	s_mov_b32 m0, s45
	s_nop 0
	global_load_lds_dwordx4 v[246:247], off
	s_waitcnt vmcnt(8)
	s_waitcnt lgkmcnt(0)
	s_barrier
	s_setprio 1
	s_waitcnt lgkmcnt(0)
	v_mfma_f32_16x16x32_bf16 v[122:125], v[164:167], v[196:199], v[122:125]
	v_mfma_f32_16x16x32_bf16 v[114:117], v[172:175], v[196:199], v[114:117]
	v_mfma_f32_16x16x32_bf16 v[106:109], v[164:167], v[204:207], v[106:109]
	v_mfma_f32_16x16x32_bf16 v[98:101], v[172:175], v[204:207], v[98:101]
	v_mfma_f32_16x16x32_bf16 v[90:93], v[164:167], v[224:227], v[90:93]
	v_mfma_f32_16x16x32_bf16 v[82:85], v[172:175], v[224:227], v[82:85]
	v_mfma_f32_16x16x32_bf16 v[74:77], v[164:167], v[232:235], v[74:77]
	v_mfma_f32_16x16x32_bf16 v[66:69], v[172:175], v[232:235], v[66:69]
	v_mfma_f32_16x16x32_bf16 v[122:125], v[168:171], v[200:203], v[122:125]
	v_mfma_f32_16x16x32_bf16 v[114:117], v[176:179], v[200:203], v[114:117]
	v_mfma_f32_16x16x32_bf16 v[106:109], v[168:171], v[220:223], v[106:109]
	v_mfma_f32_16x16x32_bf16 v[98:101], v[176:179], v[220:223], v[98:101]
	v_mfma_f32_16x16x32_bf16 v[90:93], v[168:171], v[228:231], v[90:93]
	v_mfma_f32_16x16x32_bf16 v[82:85], v[176:179], v[228:231], v[82:85]
	v_mfma_f32_16x16x32_bf16 v[74:77], v[168:171], v[236:239], v[74:77]
	v_mfma_f32_16x16x32_bf16 v[66:69], v[176:179], v[236:239], v[66:69]
	s_setprio 0
	s_setprio 1
	v_mfma_f32_16x16x32_bf16 v[126:129], v[180:183], v[196:199], v[126:129]
	v_mfma_f32_16x16x32_bf16 v[118:121], v[188:191], v[196:199], v[118:121]
	v_mfma_f32_16x16x32_bf16 v[110:113], v[180:183], v[204:207], v[110:113]
	v_mfma_f32_16x16x32_bf16 v[102:105], v[188:191], v[204:207], v[102:105]
	v_mfma_f32_16x16x32_bf16 v[94:97], v[180:183], v[224:227], v[94:97]
	v_mfma_f32_16x16x32_bf16 v[86:89], v[188:191], v[224:227], v[86:89]
	v_mfma_f32_16x16x32_bf16 v[78:81], v[180:183], v[232:235], v[78:81]
	v_mfma_f32_16x16x32_bf16 v[70:73], v[188:191], v[232:235], v[70:73]
	v_mfma_f32_16x16x32_bf16 v[126:129], v[184:187], v[200:203], v[126:129]
	v_mfma_f32_16x16x32_bf16 v[118:121], v[192:195], v[200:203], v[118:121]
	v_mfma_f32_16x16x32_bf16 v[110:113], v[184:187], v[220:223], v[110:113]
	v_mfma_f32_16x16x32_bf16 v[102:105], v[192:195], v[220:223], v[102:105]
	v_mfma_f32_16x16x32_bf16 v[94:97], v[184:187], v[228:231], v[94:97]
	v_mfma_f32_16x16x32_bf16 v[86:89], v[192:195], v[228:231], v[86:89]
	v_mfma_f32_16x16x32_bf16 v[78:81], v[184:187], v[236:239], v[78:81]
	v_mfma_f32_16x16x32_bf16 v[70:73], v[192:195], v[236:239], v[70:73]
	s_setprio 0
	s_barrier
	s_add_i32 s22, s54, s41
	v_lshl_add_u64 v[158:159], v[158:159], 0, s[2:3]
	s_mov_b32 m0, s22
	ds_read_b128 v[196:199], v162 offset:49152
	ds_read_b128 v[200:203], v162 offset:50176
	ds_read_b128 v[204:207], v162 offset:51200
	ds_read_b128 v[220:223], v162 offset:52224
	ds_read_b128 v[224:227], v162 offset:53248
	ds_read_b128 v[228:231], v162 offset:54272
	ds_read_b128 v[232:235], v162 offset:55296
	ds_read_b128 v[236:239], v162 offset:56320
	global_load_lds_dwordx4 v[158:159], off
	s_add_i32 m0, s22, 0x2000
	s_add_u32 s20, s20, 0x80080
	v_lshl_add_u64 v[158:159], v[208:209], 0, s[2:3]
	s_addc_u32 s21, s21, 0
	s_add_i32 s22, s55, s41
	global_load_lds_dwordx4 v[158:159], off
	v_lshl_add_u64 v[158:159], s[20:21], 0, v[0:1]
	s_mov_b32 m0, s22
	s_nop 0
	global_load_lds_dwordx4 v[158:159], off
	v_lshl_add_u64 v[158:159], s[20:21], 0, v[130:131]
	s_add_i32 m0, s22, 0x2000
	s_nop 0
	global_load_lds_dwordx4 v[158:159], off
	v_lshl_add_u64 v[158:159], v[216:217], 0, s[2:3]
	s_mov_b32 m0, s46
	s_nop 0
	global_load_lds_dwordx4 v[158:159], off
	v_lshl_add_u64 v[158:159], v[244:245], 0, s[2:3]
	s_mov_b32 m0, s47
	s_nop 0
	global_load_lds_dwordx4 v[158:159], off
	s_waitcnt vmcnt(8)
	s_waitcnt lgkmcnt(0)
	s_barrier
	s_setprio 1
	s_waitcnt lgkmcnt(0)
	v_mfma_f32_16x16x32_bf16 v[58:61], v[164:167], v[196:199], v[58:61]
	v_mfma_f32_16x16x32_bf16 v[50:53], v[172:175], v[196:199], v[50:53]
	v_mfma_f32_16x16x32_bf16 v[42:45], v[164:167], v[204:207], v[42:45]
	v_mfma_f32_16x16x32_bf16 v[34:37], v[172:175], v[204:207], v[34:37]
	v_mfma_f32_16x16x32_bf16 v[26:29], v[164:167], v[224:227], v[26:29]
	v_mfma_f32_16x16x32_bf16 v[18:21], v[172:175], v[224:227], v[18:21]
	v_mfma_f32_16x16x32_bf16 v[10:13], v[164:167], v[232:235], v[10:13]
	v_mfma_f32_16x16x32_bf16 v[2:5], v[172:175], v[232:235], v[2:5]
	v_mfma_f32_16x16x32_bf16 v[58:61], v[168:171], v[200:203], v[58:61]
	v_mfma_f32_16x16x32_bf16 v[50:53], v[176:179], v[200:203], v[50:53]
	v_mfma_f32_16x16x32_bf16 v[42:45], v[168:171], v[220:223], v[42:45]
	v_mfma_f32_16x16x32_bf16 v[34:37], v[176:179], v[220:223], v[34:37]
	v_mfma_f32_16x16x32_bf16 v[26:29], v[168:171], v[228:231], v[26:29]
	v_mfma_f32_16x16x32_bf16 v[18:21], v[176:179], v[228:231], v[18:21]
	v_mfma_f32_16x16x32_bf16 v[10:13], v[168:171], v[236:239], v[10:13]
	v_mfma_f32_16x16x32_bf16 v[2:5], v[176:179], v[236:239], v[2:5]
	s_setprio 0
	s_setprio 1
	v_mfma_f32_16x16x32_bf16 v[62:65], v[180:183], v[196:199], v[62:65]
	v_mfma_f32_16x16x32_bf16 v[54:57], v[188:191], v[196:199], v[54:57]
	v_mfma_f32_16x16x32_bf16 v[46:49], v[180:183], v[204:207], v[46:49]
	v_mfma_f32_16x16x32_bf16 v[38:41], v[188:191], v[204:207], v[38:41]
	v_mfma_f32_16x16x32_bf16 v[30:33], v[180:183], v[224:227], v[30:33]
	v_mfma_f32_16x16x32_bf16 v[22:25], v[188:191], v[224:227], v[22:25]
	v_mfma_f32_16x16x32_bf16 v[14:17], v[180:183], v[232:235], v[14:17]
	v_mfma_f32_16x16x32_bf16 v[6:9], v[188:191], v[232:235], v[6:9]
	v_mfma_f32_16x16x32_bf16 v[62:65], v[184:187], v[200:203], v[62:65]
	v_mfma_f32_16x16x32_bf16 v[54:57], v[192:195], v[200:203], v[54:57]
	v_mfma_f32_16x16x32_bf16 v[46:49], v[184:187], v[220:223], v[46:49]
	v_mfma_f32_16x16x32_bf16 v[38:41], v[192:195], v[220:223], v[38:41]
	v_mfma_f32_16x16x32_bf16 v[30:33], v[184:187], v[228:231], v[30:33]
	v_mfma_f32_16x16x32_bf16 v[22:25], v[192:195], v[228:231], v[22:25]
	v_mfma_f32_16x16x32_bf16 v[14:17], v[184:187], v[236:239], v[14:17]
	v_mfma_f32_16x16x32_bf16 v[6:9], v[192:195], v[236:239], v[6:9]
	s_setprio 0
	s_barrier
	s_add_i32 s53, s53, 2
	s_add_u32 s18, s18, 0x100
	s_addc_u32 s19, s19, 0
	s_add_u32 s51, s51, 0x100
	s_addc_u32 s52, s52, 0
	s_cmp_gt_u32 s53, 29
	s_cbranch_scc1 .Lpeel_done_4
